# early gating unit: no extra L1 invalidate before it (the D1 seam's invalidate already precedes every load of those lines)
# baseline (speedup 1.0000x reference)
; template <class T> __device__ __forceinline__ T* as_global(T* p) { return (T*)(GAS T*)p; }
; #define SEAM(k) do { if ((k) + 1 < hi) { if ((k) == 0) grid.sync(); else { xcd_barrier(bar); if (DUP & 4) xcd_barrier(bar); } } } while (0)
; #define SEAM(k) do { } while (0)
; #define WSBASE() GAS unsigned char* wsg_ = (GAS unsigned char*)a.ws; asm volatile("" : "+s"(wsg_)); unsigned char* ws = (unsigned char*)wsg_; i64* stats = (i64*)(ws + WS_STATS); i64* st = stats + (size_t)(6 * l) * MTOK; unsigned char* wl = ws + WS_W + (size_t)l * WL_STRIDE; (void)st; (void)wl
; __global__ void __launch_bounds__(NWAVES * 64, 2) fwd_kernel(Args a) {
;     ...
;                 IDLE_CONVERT(1);
;                 SEAM(pb + 2);
;             }
;             if (IN(pb + 3)) {
;                 const int tid = threadIdx.x, lane = tid & 63, wave = __builtin_amdgcn_readfirstlane(tid >> 6);
;                 if (!(SKIP & 4)) { WSBASE();
;                   for (int u = cu; u < 256; u += G) { const int j = u >> 3, bh = (u & 7) * 2 + (j >> 4), blk = j & 15;
;                     attn_unit(lds, bh >> 3, bh & 7, blk, (const bf16_t*)(ws + WS_Q), (const bf16_t*)(ws + WS_K), (const bf16_t*)(ws + WS_VT1), (const bf16_t*)(ws + WS_VT4), (const bf16_t*)(ws + WS_VT16),
;                               (bf16_t*)(ws + WS_MIX), st + 2 * MTOK, wave, lane);
;                     if (DUP & 1) attn_unit(lds, bh >> 3, bh & 7, blk, (const bf16_t*)(ws + WS_Q), (const bf16_t*)(ws + WS_K), (const bf16_t*)(ws + WS_VT1), (const bf16_t*)(ws + WS_VT4), (const bf16_t*)(ws + WS_VT16),
;                               (bf16_t*)(ws + WS_MIX), stats + (size_t)30 * MTOK, wave, lane); } }
;                 if (!(SKIP & 8)) { WSBASE();
;                   for (int u = cu; u < MTOK / 128; u += G) for (int rp = 0; rp < ((DUP & 2) ? 2 : 1); ++rp)
;                     sgu_unit(lds, u * 128, (const bf16_t*)(ws + WS_GT), (const bf16_t*)(ws + WS_U), (const bf16_t*)(ws + WS_SGUW) + (size_t)l * 4 * 16384, as_global(a.in[10]) + l * 512, as_global(a.in[7]) + l * DH, as_global(a.in[8]) + l * DH,
;                              st + 3 * MTOK, st + 4 * MTOK, (bf16_t*)(ws + WS_MIX), wave, lane); }
.Les_polled:
	s_mov_b64 exec, s[4:5]
	s_barrier
	v_writelane_b32 v255, s46, 10
	v_writelane_b32 v255, s47, 11
	v_writelane_b32 v255, s48, 12
	v_writelane_b32 v255, s49, 13
	v_writelane_b32 v255, s50, 14
	v_writelane_b32 v255, s51, 15
	v_writelane_b32 v255, s52, 16
	v_writelane_b32 v255, s53, 17
	s_branch .Lsgu_early
